# in-proj 44 column tiles for all layers + per-workgroup MFMA block (K split over 8 waves, LDS reduction, loops over row chunks) for the 48 value-residual columns; rstd_table load pipelining; PRM load o
# baseline (speedup 1.0000x reference)
; #define LAS __attribute__((address_space(3)))
;     DI void init(const bf16* A_, int lda, const bf16* B_, int ldb, int nM, int nN, int K, int G_, int c_) { T.init(nM, nN); G = G_; c = c_; nt = K / BK; A = (const char*)A_; B = (const char*)B_; ta = (size_t)BM * lda * 2; tb = (size_t)BM * ldb * 2; }
;     DI void init(const bf16* A_, int lda, const bf16* B_, int ldb, int nM, int nN, int G_, int c_) { T.init(nM, nN); G = G_; c = c_; A = (const char*)A_; B = (const char*)B_; ta = (size_t)BM * lda * 2; tb = (size_t)BM * ldb * 2; }
; #define SEAM(k) do { if (IN((k) + 1) && IN(k)) xcd_barrier(bar); } while (0)
; #define FRAME() const CAS Args* ap; const Frame F = make_frame(lds, ap, wv); const CAS Args& A = *ap; (void)A
; __global__ void __launch_bounds__(512, 2) trunk_fwd(Args args_unused) {
;     ...
;         if (PHEN(1) && IN(s0 + 1)) { FRAME();
;             const int nN = (l == 0) ? 44 : 45;
;             const LAS float* rs = rstd_table(F);
;             SchedPlain S; S.init((const bf16*)F.out, XP, (const bf16*)lw(F, l, LW_WIN), D, M / BM, nN, D, F.G, F.bid);
;             EpiInproj E{(bf16*)(F.ws + WS_R2), A.in[3] + (size_t)l * 6144, (bf16*)(F.ws + WS_ZS5), rs};
;             gemm_phase<EpiInproj, SchedPlain>(F.lds, F.wave, XP, D, S, E);
;             SEAM(s0 + 1);
.LBB0_489:
	s_cmp_eq_u32 s71, 0
	s_cbranch_scc1 .Lvres_done
	s_load_dwordx4 s[4:7], s[88:89], 0x130
	v_mbcnt_lo_u32_b32 v238, -1, 0
	v_mbcnt_hi_u32_b32 v238, -1, v238
	v_readlane_b32 s0, v252, 0
	s_nop 0
	s_mov_b32 m0, s0
.Lvres_chunk:
	s_mov_b32 s0, m0
	v_and_b32_e32 v239, 15, v238
	v_lshrrev_b32_e32 v240, 4, v238
	s_lshl_b32 s0, s0, 6
	s_and_b32 s1, s90, 3
	s_lshl_b32 s1, s1, 4
	s_add_i32 s1, s0, s1
	v_add_u32_e32 v184, s1, v239
	v_lshlrev_b32_e32 v241, 7, v184
	v_mul_u32_u24_e32 v242, 0x5a00, v184
	v_lshl_add_u32 v242, v240, 3, v242
	v_add_u32_e32 v243, s0, v239
	v_lshlrev_b32_e32 v243, 12, v243
	v_lshl_add_u32 v243, v240, 4, v243
	s_lshl_b32 s2, s90, 9
	v_add_u32_e32 v243, s2, v243
	v_add_u32_e32 v244, 0x10000, v243
	v_add_u32_e32 v245, 0x20000, v243
	v_add_u32_e32 v246, 0x30000, v243
	v_lshlrev_b32_e32 v247, 12, v239
	v_lshl_add_u32 v247, v240, 4, v247
	v_add_u32_e32 v247, s2, v247
	v_add_u32_e32 v248, 0x10000, v247
	v_add_u32_e32 v249, 0x20000, v247
	s_mul_i32 s17, s71, 0x7eca000
	s_waitcnt lgkmcnt(0)
	s_add_u32 s100, s6, 0x49c28000
	s_addc_u32 s101, s7, 0
	global_load_dwordx4 v[196:199], v241, s[100:101] offset:32
	global_load_dwordx4 v[200:203], v241, s[100:101] offset:48
	global_load_dwordx4 v[204:207], v241, s[100:101]
	global_load_dwordx4 v[208:211], v241, s[100:101] offset:16
	global_load_dwordx4 v[212:215], v241, s[100:101] offset:96
	global_load_dwordx4 v[216:219], v241, s[100:101] offset:112
	global_load_dwordx4 v[220:223], v241, s[100:101] offset:64
	global_load_dwordx4 v[234:237], v241, s[100:101] offset:80
	s_add_u32 s0, s6, s17
	s_addc_u32 s1, s7, 0
	s_add_u32 s0, s0, 0x2d00000
	s_addc_u32 s1, s1, 0
	s_add_u32 s16, s6, 0x23c2d800
	s_addc_u32 s17, s7, 0
	global_load_dwordx4 v[0:3], v243, s[4:5]
	global_load_dwordx4 v[4:7], v244, s[4:5]
	global_load_dwordx4 v[8:11], v245, s[4:5]
	global_load_dwordx4 v[12:15], v246, s[4:5]
	global_load_dwordx4 v[16:19], v247, s[0:1]
	global_load_dwordx4 v[20:23], v248, s[0:1]
	global_load_dwordx4 v[24:27], v249, s[0:1]
	global_load_dwordx4 v[28:31], v243, s[4:5] offset:64
	global_load_dwordx4 v[32:35], v244, s[4:5] offset:64
	global_load_dwordx4 v[36:39], v245, s[4:5] offset:64
	global_load_dwordx4 v[40:43], v246, s[4:5] offset:64
	global_load_dwordx4 v[44:47], v247, s[0:1] offset:64
	global_load_dwordx4 v[48:51], v248, s[0:1] offset:64
	global_load_dwordx4 v[52:55], v249, s[0:1] offset:64
	global_load_dwordx4 v[56:59], v243, s[4:5] offset:128
	global_load_dwordx4 v[60:63], v244, s[4:5] offset:128
	global_load_dwordx4 v[64:67], v245, s[4:5] offset:128
	global_load_dwordx4 v[68:71], v246, s[4:5] offset:128
	global_load_dwordx4 v[72:75], v247, s[0:1] offset:128
	global_load_dwordx4 v[76:79], v248, s[0:1] offset:128
	global_load_dwordx4 v[80:83], v249, s[0:1] offset:128
	global_load_dwordx4 v[84:87], v243, s[4:5] offset:192
	global_load_dwordx4 v[88:91], v244, s[4:5] offset:192
	global_load_dwordx4 v[92:95], v245, s[4:5] offset:192
	global_load_dwordx4 v[96:99], v246, s[4:5] offset:192
	global_load_dwordx4 v[100:103], v247, s[0:1] offset:192
	global_load_dwordx4 v[104:107], v248, s[0:1] offset:192
	global_load_dwordx4 v[108:111], v249, s[0:1] offset:192
	global_load_dwordx4 v[112:115], v243, s[4:5] offset:256
	global_load_dwordx4 v[116:119], v244, s[4:5] offset:256
	global_load_dwordx4 v[120:123], v245, s[4:5] offset:256
	global_load_dwordx4 v[124:127], v246, s[4:5] offset:256
	global_load_dwordx4 v[128:131], v247, s[0:1] offset:256
	global_load_dwordx4 v[132:135], v248, s[0:1] offset:256
	global_load_dwordx4 v[136:139], v249, s[0:1] offset:256
	s_waitcnt vmcnt(28)
	v_mfma_f32_16x16x32_bf16 v[140:143], v[16:19], v[0:3], 0
	v_mfma_f32_16x16x32_bf16 v[144:147], v[20:23], v[0:3], 0
	v_mfma_f32_16x16x32_bf16 v[148:151], v[24:27], v[0:3], 0
	v_mfma_f32_16x16x32_bf16 v[152:155], v[16:19], v[4:7], 0
	v_mfma_f32_16x16x32_bf16 v[156:159], v[20:23], v[4:7], 0
	v_mfma_f32_16x16x32_bf16 v[160:163], v[24:27], v[4:7], 0
	v_mfma_f32_16x16x32_bf16 v[164:167], v[16:19], v[8:11], 0
	v_mfma_f32_16x16x32_bf16 v[168:171], v[20:23], v[8:11], 0
	v_mfma_f32_16x16x32_bf16 v[172:175], v[24:27], v[8:11], 0
	v_mfma_f32_16x16x32_bf16 v[176:179], v[16:19], v[12:15], 0
	v_mfma_f32_16x16x32_bf16 v[180:183], v[20:23], v[12:15], 0
	v_mfma_f32_16x16x32_bf16 v[188:191], v[24:27], v[12:15], 0
	global_load_dwordx4 v[0:3], v243, s[4:5] offset:320
	global_load_dwordx4 v[4:7], v244, s[4:5] offset:320
	global_load_dwordx4 v[8:11], v245, s[4:5] offset:320
	global_load_dwordx4 v[12:15], v246, s[4:5] offset:320
	global_load_dwordx4 v[16:19], v247, s[0:1] offset:320
	global_load_dwordx4 v[20:23], v248, s[0:1] offset:320
	global_load_dwordx4 v[24:27], v249, s[0:1] offset:320
	s_waitcnt vmcnt(28)
	v_mfma_f32_16x16x32_bf16 v[140:143], v[44:47], v[28:31], v[140:143]
	v_mfma_f32_16x16x32_bf16 v[144:147], v[48:51], v[28:31], v[144:147]
	v_mfma_f32_16x16x32_bf16 v[148:151], v[52:55], v[28:31], v[148:151]
	v_mfma_f32_16x16x32_bf16 v[152:155], v[44:47], v[32:35], v[152:155]
	v_mfma_f32_16x16x32_bf16 v[156:159], v[48:51], v[32:35], v[156:159]
	v_mfma_f32_16x16x32_bf16 v[160:163], v[52:55], v[32:35], v[160:163]
	v_mfma_f32_16x16x32_bf16 v[164:167], v[44:47], v[36:39], v[164:167]
	v_mfma_f32_16x16x32_bf16 v[168:171], v[48:51], v[36:39], v[168:171]
	v_mfma_f32_16x16x32_bf16 v[172:175], v[52:55], v[36:39], v[172:175]
	v_mfma_f32_16x16x32_bf16 v[176:179], v[44:47], v[40:43], v[176:179]
	v_mfma_f32_16x16x32_bf16 v[180:183], v[48:51], v[40:43], v[180:183]
	v_mfma_f32_16x16x32_bf16 v[188:191], v[52:55], v[40:43], v[188:191]
	global_load_dwordx4 v[28:31], v243, s[4:5] offset:384
	global_load_dwordx4 v[32:35], v244, s[4:5] offset:384
	global_load_dwordx4 v[36:39], v245, s[4:5] offset:384
	global_load_dwordx4 v[40:43], v246, s[4:5] offset:384
	global_load_dwordx4 v[44:47], v247, s[0:1] offset:384
	global_load_dwordx4 v[48:51], v248, s[0:1] offset:384
	global_load_dwordx4 v[52:55], v249, s[0:1] offset:384
	s_waitcnt vmcnt(28)
; #define LAS __attribute__((address_space(3)))
;     DI void init(const bf16* A_, int lda, const bf16* B_, int ldb, int nM, int nN, int K, int G_, int c_) { T.init(nM, nN); G = G_; c = c_; nt = K / BK; A = (const char*)A_; B = (const char*)B_; ta = (size_t)BM * lda * 2; tb = (size_t)BM * ldb * 2; }
;     DI void init(const bf16* A_, int lda, const bf16* B_, int ldb, int nM, int nN, int G_, int c_) { T.init(nM, nN); G = G_; c = c_; A = (const char*)A_; B = (const char*)B_; ta = (size_t)BM * lda * 2; tb = (size_t)BM * ldb * 2; }
; #define SEAM(k) do { if (IN((k) + 1) && IN(k)) xcd_barrier(bar); } while (0)
; #define FRAME() const CAS Args* ap; const Frame F = make_frame(lds, ap, wv); const CAS Args& A = *ap; (void)A
; __global__ void __launch_bounds__(512, 2) trunk_fwd(Args args_unused) {
;     ...
;         if (PHEN(1) && IN(s0 + 1)) { FRAME();
;             const int nN = (l == 0) ? 44 : 45;
;             const LAS float* rs = rstd_table(F);
;             SchedPlain S; S.init((const bf16*)F.out, XP, (const bf16*)lw(F, l, LW_WIN), D, M / BM, nN, D, F.G, F.bid);
;             EpiInproj E{(bf16*)(F.ws + WS_R2), A.in[3] + (size_t)l * 6144, (bf16*)(F.ws + WS_ZS5), rs};
;             gemm_phase<EpiInproj, SchedPlain>(F.lds, F.wave, XP, D, S, E);
;             SEAM(s0 + 1);
	v_mfma_f32_16x16x32_bf16 v[140:143], v[72:75], v[56:59], v[140:143]
	v_mfma_f32_16x16x32_bf16 v[144:147], v[76:79], v[56:59], v[144:147]
	v_mfma_f32_16x16x32_bf16 v[148:151], v[80:83], v[56:59], v[148:151]
	v_mfma_f32_16x16x32_bf16 v[152:155], v[72:75], v[60:63], v[152:155]
	v_mfma_f32_16x16x32_bf16 v[156:159], v[76:79], v[60:63], v[156:159]
	v_mfma_f32_16x16x32_bf16 v[160:163], v[80:83], v[60:63], v[160:163]
	v_mfma_f32_16x16x32_bf16 v[164:167], v[72:75], v[64:67], v[164:167]
	v_mfma_f32_16x16x32_bf16 v[168:171], v[76:79], v[64:67], v[168:171]
	v_mfma_f32_16x16x32_bf16 v[172:175], v[80:83], v[64:67], v[172:175]
	v_mfma_f32_16x16x32_bf16 v[176:179], v[72:75], v[68:71], v[176:179]
	v_mfma_f32_16x16x32_bf16 v[180:183], v[76:79], v[68:71], v[180:183]
	v_mfma_f32_16x16x32_bf16 v[188:191], v[80:83], v[68:71], v[188:191]
	global_load_dwordx4 v[56:59], v243, s[4:5] offset:448
	global_load_dwordx4 v[60:63], v244, s[4:5] offset:448
	global_load_dwordx4 v[64:67], v245, s[4:5] offset:448
	global_load_dwordx4 v[68:71], v246, s[4:5] offset:448
	global_load_dwordx4 v[72:75], v247, s[0:1] offset:448
	global_load_dwordx4 v[76:79], v248, s[0:1] offset:448
	global_load_dwordx4 v[80:83], v249, s[0:1] offset:448
	s_waitcnt vmcnt(28)
	v_mfma_f32_16x16x32_bf16 v[140:143], v[100:103], v[84:87], v[140:143]
	v_mfma_f32_16x16x32_bf16 v[144:147], v[104:107], v[84:87], v[144:147]
	v_mfma_f32_16x16x32_bf16 v[148:151], v[108:111], v[84:87], v[148:151]
	v_mfma_f32_16x16x32_bf16 v[152:155], v[100:103], v[88:91], v[152:155]
	v_mfma_f32_16x16x32_bf16 v[156:159], v[104:107], v[88:91], v[156:159]
	v_mfma_f32_16x16x32_bf16 v[160:163], v[108:111], v[88:91], v[160:163]
	v_mfma_f32_16x16x32_bf16 v[164:167], v[100:103], v[92:95], v[164:167]
	v_mfma_f32_16x16x32_bf16 v[168:171], v[104:107], v[92:95], v[168:171]
	v_mfma_f32_16x16x32_bf16 v[172:175], v[108:111], v[92:95], v[172:175]
	v_mfma_f32_16x16x32_bf16 v[176:179], v[100:103], v[96:99], v[176:179]
	v_mfma_f32_16x16x32_bf16 v[180:183], v[104:107], v[96:99], v[180:183]
	v_mfma_f32_16x16x32_bf16 v[188:191], v[108:111], v[96:99], v[188:191]
	s_waitcnt vmcnt(21)
	v_mfma_f32_16x16x32_bf16 v[140:143], v[128:131], v[112:115], v[140:143]
	v_mfma_f32_16x16x32_bf16 v[144:147], v[132:135], v[112:115], v[144:147]
	v_mfma_f32_16x16x32_bf16 v[148:151], v[136:139], v[112:115], v[148:151]
	v_mfma_f32_16x16x32_bf16 v[152:155], v[128:131], v[116:119], v[152:155]
	v_mfma_f32_16x16x32_bf16 v[156:159], v[132:135], v[116:119], v[156:159]
	v_mfma_f32_16x16x32_bf16 v[160:163], v[136:139], v[116:119], v[160:163]
	v_mfma_f32_16x16x32_bf16 v[164:167], v[128:131], v[120:123], v[164:167]
	v_mfma_f32_16x16x32_bf16 v[168:171], v[132:135], v[120:123], v[168:171]
	v_mfma_f32_16x16x32_bf16 v[172:175], v[136:139], v[120:123], v[172:175]
	v_mfma_f32_16x16x32_bf16 v[176:179], v[128:131], v[124:127], v[176:179]
	v_mfma_f32_16x16x32_bf16 v[180:183], v[132:135], v[124:127], v[180:183]
	v_mfma_f32_16x16x32_bf16 v[188:191], v[136:139], v[124:127], v[188:191]
	s_waitcnt vmcnt(14)
	v_mfma_f32_16x16x32_bf16 v[140:143], v[16:19], v[0:3], v[140:143]
	v_mfma_f32_16x16x32_bf16 v[144:147], v[20:23], v[0:3], v[144:147]
	v_mfma_f32_16x16x32_bf16 v[148:151], v[24:27], v[0:3], v[148:151]
	v_mfma_f32_16x16x32_bf16 v[152:155], v[16:19], v[4:7], v[152:155]
	v_mfma_f32_16x16x32_bf16 v[156:159], v[20:23], v[4:7], v[156:159]
	v_mfma_f32_16x16x32_bf16 v[160:163], v[24:27], v[4:7], v[160:163]
	v_mfma_f32_16x16x32_bf16 v[164:167], v[16:19], v[8:11], v[164:167]
	v_mfma_f32_16x16x32_bf16 v[168:171], v[20:23], v[8:11], v[168:171]
	v_mfma_f32_16x16x32_bf16 v[172:175], v[24:27], v[8:11], v[172:175]
	v_mfma_f32_16x16x32_bf16 v[176:179], v[16:19], v[12:15], v[176:179]
	v_mfma_f32_16x16x32_bf16 v[180:183], v[20:23], v[12:15], v[180:183]
	v_mfma_f32_16x16x32_bf16 v[188:191], v[24:27], v[12:15], v[188:191]
	s_waitcnt vmcnt(7)
	v_mfma_f32_16x16x32_bf16 v[140:143], v[44:47], v[28:31], v[140:143]
	v_mfma_f32_16x16x32_bf16 v[144:147], v[48:51], v[28:31], v[144:147]
	v_mfma_f32_16x16x32_bf16 v[148:151], v[52:55], v[28:31], v[148:151]
	v_mfma_f32_16x16x32_bf16 v[152:155], v[44:47], v[32:35], v[152:155]
	v_mfma_f32_16x16x32_bf16 v[156:159], v[48:51], v[32:35], v[156:159]
	v_mfma_f32_16x16x32_bf16 v[160:163], v[52:55], v[32:35], v[160:163]
	v_mfma_f32_16x16x32_bf16 v[164:167], v[44:47], v[36:39], v[164:167]
	v_mfma_f32_16x16x32_bf16 v[168:171], v[48:51], v[36:39], v[168:171]
	v_mfma_f32_16x16x32_bf16 v[172:175], v[52:55], v[36:39], v[172:175]
	v_mfma_f32_16x16x32_bf16 v[176:179], v[44:47], v[40:43], v[176:179]
	v_mfma_f32_16x16x32_bf16 v[180:183], v[48:51], v[40:43], v[180:183]
	v_mfma_f32_16x16x32_bf16 v[188:191], v[52:55], v[40:43], v[188:191]
	s_waitcnt vmcnt(0)
	v_mfma_f32_16x16x32_bf16 v[140:143], v[72:75], v[56:59], v[140:143]
	v_mfma_f32_16x16x32_bf16 v[144:147], v[76:79], v[56:59], v[144:147]
	v_mfma_f32_16x16x32_bf16 v[148:151], v[80:83], v[56:59], v[148:151]
	v_mfma_f32_16x16x32_bf16 v[152:155], v[72:75], v[60:63], v[152:155]
	v_mfma_f32_16x16x32_bf16 v[156:159], v[76:79], v[60:63], v[156:159]
	v_mfma_f32_16x16x32_bf16 v[160:163], v[80:83], v[60:63], v[160:163]
	v_mfma_f32_16x16x32_bf16 v[164:167], v[72:75], v[64:67], v[164:167]
	v_mfma_f32_16x16x32_bf16 v[168:171], v[76:79], v[64:67], v[168:171]
	v_mfma_f32_16x16x32_bf16 v[172:175], v[80:83], v[64:67], v[172:175]
	v_mfma_f32_16x16x32_bf16 v[176:179], v[72:75], v[68:71], v[176:179]
	v_mfma_f32_16x16x32_bf16 v[180:183], v[76:79], v[68:71], v[180:183]
	v_mfma_f32_16x16x32_bf16 v[188:191], v[80:83], v[68:71], v[188:191]
	v_lshlrev_b32_e32 v0, 4, v238
	s_lshl_b32 s2, s90, 10
	v_add_u32_e32 v1, s2, v0
	v_add_u32_e32 v2, 0xc000, v1
	s_nop 15
	s_nop 15
	ds_write_b128 v1, v[140:143]
	ds_write_b128 v1, v[144:147] offset:8192
	ds_write_b128 v1, v[148:151] offset:16384
	ds_write_b128 v1, v[152:155] offset:24576
	ds_write_b128 v1, v[156:159] offset:32768
	ds_write_b128 v1, v[160:163] offset:40960
	ds_write_b128 v2, v[164:167]
	ds_write_b128 v2, v[168:171] offset:8192
	ds_write_b128 v2, v[172:175] offset:16384
	ds_write_b128 v2, v[176:179] offset:24576
	ds_write_b128 v2, v[180:183] offset:32768
	ds_write_b128 v2, v[188:191] offset:40960
	s_waitcnt lgkmcnt(0)
	s_barrier
; #define GAS __attribute__((address_space(1)))
; DI unsigned pk2(float lo, float hi) { f32x2 v = {lo, hi}; bf16x2_t r = __builtin_convertvector(v, bf16x2_t); return __builtin_bit_cast(unsigned, r); }
; DI float sigmoidf_(float x) { return __builtin_amdgcn_rcpf(1.f + __expf(-x)); }
; #define SB() __builtin_amdgcn_sched_barrier(0)
;     DI bool operator()(AccT& acc, const Unit& u, int wr, int wc, int fr, int fq) const {
;     ...
;                     f32x4 v0 = acc[ai][bj][m][0] * rsv[ai][m], v1 = acc[ai][bj][m][1] * rsv[ai][m];
;                     if (gate) { v0 += b0; v1 += b1;
; #pragma unroll
;                         for (int e = 0; e < 4; ++e) { v0[e] = sigmoidf_(v0[e]); v1[e] = sigmoidf_(v1[e]); } }
;                     u32x4 w; w.x = pk2(v0[0], v0[1]); w.y = pk2(v0[2], v0[3]); w.z = pk2(v1[0], v1[1]); w.w = pk2(v1[2], v1[3]);
;                     if (s5c) *(GAS u32x4*)(ZS5 + ((size_t)(col >> 4) * M + (row0 + ai * HALF + m * 16)) * 16 + (col & 8)) = w;
;                     else *(GAS u32x4*)(Z + (size_t)(row0 + ai * HALF + m * 16) * ZP + col) = w;
; DI const LAS float* rstd_table(const Frame& F) {
;     ...
; #pragma unroll
;         for (int q = 0; q < 8; ++q) p[q] = ((const GAS f32x4*)(P + (size_t)r * 32))[q];
;         SB();
;         f32x4 t = (p[0] + p[1]) + (p[2] + p[3]) + ((p[4] + p[5]) + (p[6] + p[7]));
;         tab[r] = 1.f / sqrtf(((t[0] + t[1]) + (t[2] + t[3])) * (1.f / D) + NORM_EPS);
	s_and_b32 s2, s90, 3
	s_mul_i32 s2, s2, 3
	s_lshr_b32 s3, s90, 2
	s_add_i32 s98, s2, s3
	s_add_i32 s99, s2, 2
	s_lshl_b32 s98, s98, 13
	s_lshl_b32 s99, s99, 13
	v_add_u32_e32 v3, s98, v0
	v_add_u32_e32 v4, s99, v0
	ds_read_b128 v[8:11], v3
	ds_read_b128 v[12:15], v3 offset:1024
	ds_read_b128 v[16:19], v3 offset:2048
	ds_read_b128 v[20:23], v3 offset:3072
	ds_read_b128 v[24:27], v3 offset:4096
	ds_read_b128 v[28:31], v3 offset:5120
	ds_read_b128 v[32:35], v3 offset:6144
	ds_read_b128 v[36:39], v3 offset:7168
	ds_read_b128 v[40:43], v4
	ds_read_b128 v[44:47], v4 offset:1024
	ds_read_b128 v[48:51], v4 offset:2048
	ds_read_b128 v[52:55], v4 offset:3072
	ds_read_b128 v[56:59], v4 offset:4096
	ds_read_b128 v[60:63], v4 offset:5120
	ds_read_b128 v[64:67], v4 offset:6144
	ds_read_b128 v[68:71], v4 offset:7168
	v_pk_add_f32 v[206:207], v[206:207], v[210:211]
	v_pk_add_f32 v[204:205], v[204:205], v[208:209]
	v_pk_add_f32 v[198:199], v[198:199], v[202:203]
	v_pk_add_f32 v[196:197], v[196:197], v[200:201]
	v_pk_add_f32 v[198:199], v[206:207], v[198:199]
	v_pk_add_f32 v[196:197], v[204:205], v[196:197]
	v_pk_add_f32 v[200:201], v[222:223], v[236:237]
	v_pk_add_f32 v[202:203], v[220:221], v[234:235]
	v_pk_add_f32 v[204:205], v[214:215], v[218:219]
	v_pk_add_f32 v[206:207], v[212:213], v[216:217]
	v_pk_add_f32 v[200:201], v[200:201], v[204:205]
	v_pk_add_f32 v[202:203], v[202:203], v[206:207]
	v_pk_add_f32 v[198:199], v[198:199], v[200:201]
	v_pk_add_f32 v[196:197], v[196:197], v[202:203]
	s_nop 0
	v_pk_mov_b32 v[200:201], v[196:197], v[198:199] op_sel:[1,0]
	v_mov_b32_e32 v197, v199
	v_pk_add_f32 v[196:197], v[200:201], v[196:197]
	s_nop 0
	v_add_f32_e32 v196, v196, v197
	v_fmamk_f32 v196, v196, 0x3a000000, v225
	v_mul_f32_e32 v197, 0x4f800000, v196
	v_cmp_gt_f32_e32 vcc, 0xf800000, v196
	s_nop 1
	v_cndmask_b32_e32 v196, v196, v197, vcc
	v_sqrt_f32_e32 v197, v196
	s_nop 0
	v_add_u32_e32 v198, -1, v197
	v_fma_f32 v199, -v198, v197, v196
	v_cmp_ge_f32_e64 s[100:101], 0, v199
	v_add_u32_e32 v199, 1, v197
	s_nop 0
	v_cndmask_b32_e64 v198, v197, v198, s[100:101]
	v_fma_f32 v197, -v199, v197, v196
	v_cmp_lt_f32_e64 s[100:101], 0, v197
	s_nop 1
	v_cndmask_b32_e64 v197, v198, v199, s[100:101]
	v_mul_f32_e32 v198, 0x37800000, v197
	v_cndmask_b32_e32 v197, v197, v198, vcc
	v_cmp_class_f32_e32 vcc, v196, v226
	s_nop 1
	v_cndmask_b32_e32 v196, v197, v196, vcc
	v_div_scale_f32 v197, s[100:101], v196, v196, 1.0
	v_rcp_f32_e32 v198, v197
	s_nop 0
	v_fma_f32 v199, -v197, v198, 1.0
	v_fmac_f32_e32 v198, v199, v198
	v_div_scale_f32 v199, vcc, 1.0, v196, 1.0
	v_mul_f32_e32 v200, v199, v198
	v_fma_f32 v201, -v197, v200, v199
	v_fmac_f32_e32 v200, v201, v198
	v_fma_f32 v197, -v197, v200, v199
	v_div_fmas_f32 v197, v197, v198, v200
	v_div_fixup_f32 v196, v197, v196, 1.0
	s_waitcnt lgkmcnt(0)
	v_pk_add_f32 v[8:9], v[8:9], v[12:13]
	v_pk_add_f32 v[10:11], v[10:11], v[14:15]
	v_pk_add_f32 v[16:17], v[16:17], v[20:21]
	v_pk_add_f32 v[18:19], v[18:19], v[22:23]
	v_pk_add_f32 v[24:25], v[24:25], v[28:29]
	v_pk_add_f32 v[26:27], v[26:27], v[30:31]
	v_pk_add_f32 v[32:33], v[32:33], v[36:37]
	v_pk_add_f32 v[34:35], v[34:35], v[38:39]
	v_pk_add_f32 v[8:9], v[8:9], v[16:17]
	v_pk_add_f32 v[10:11], v[10:11], v[18:19]
	v_pk_add_f32 v[24:25], v[24:25], v[32:33]
	v_pk_add_f32 v[26:27], v[26:27], v[34:35]
	v_pk_add_f32 v[8:9], v[8:9], v[24:25]
	v_pk_add_f32 v[10:11], v[10:11], v[26:27]
	v_pk_add_f32 v[40:41], v[40:41], v[44:45]
	v_pk_add_f32 v[42:43], v[42:43], v[46:47]
	v_pk_add_f32 v[48:49], v[48:49], v[52:53]
	v_pk_add_f32 v[50:51], v[50:51], v[54:55]
	v_pk_add_f32 v[56:57], v[56:57], v[60:61]
	v_pk_add_f32 v[58:59], v[58:59], v[62:63]
	v_pk_add_f32 v[64:65], v[64:65], v[68:69]
	v_pk_add_f32 v[66:67], v[66:67], v[70:71]
	v_pk_add_f32 v[40:41], v[40:41], v[48:49]
	v_pk_add_f32 v[42:43], v[42:43], v[50:51]
	v_pk_add_f32 v[56:57], v[56:57], v[64:65]
	v_pk_add_f32 v[58:59], v[58:59], v[66:67]
	v_pk_add_f32 v[40:41], v[40:41], v[56:57]
	v_pk_add_f32 v[42:43], v[42:43], v[58:59]
	v_mul_f32_e32 v8, v8, v196
	v_mul_f32_e32 v9, v9, v196
	v_mul_f32_e32 v10, v10, v196
	v_mul_f32_e32 v11, v11, v196
	v_mul_f32_e32 v40, v40, v196
	v_mul_f32_e32 v41, v41, v196
	v_mul_f32_e32 v42, v42, v196
	v_mul_f32_e32 v43, v43, v196
	v_cvt_pk_bf16_f32 v8, v8, v9
	v_cvt_pk_bf16_f32 v9, v10, v11
	v_cvt_pk_bf16_f32 v40, v40, v41
	v_cvt_pk_bf16_f32 v41, v42, v43
	s_lshl_b32 s3, s3, 5
	v_add_u32_e32 v5, s3, v242
	global_store_dwordx2 v5, v[8:9], s[16:17]
	global_store_dwordx2 v242, v[40:41], s[16:17] offset:64
	s_load_dword s2, s[88:89], 0x148
	s_waitcnt lgkmcnt(0)
	s_add_i32 s2, s2, m0
	s_mov_b32 m0, s2
	s_barrier
	s_cmpk_lt_u32 s2, 0x100
	s_cbranch_scc1 .Lvres_chunk
